# v022: GQA attention loop-edge rotation (LDS read address setup hoisted to loop bottom) + static wave priority for waves 4-7
# baseline (speedup 1.0000x reference)
; #define LAS __attribute__((address_space(3)))
; __device__ __forceinline__ int crow(int r, int hi) { return (r & 3) + 8 * (r >> 2) + 4 * hi; }
; template <int DK>
; __device__ __forceinline__ void attn_unit(LAS unsigned char* lds, const GAS bf16* Qp, const GAS bf16* Kp, const GAS bf16* Vp, GAS bf16* Yp, int b, int j, int nkeys, int tid, int lane, int wave) {
;     ...
;           for (int d0 = 0; d0 < ND; ++d0) {
;               if (d0 + 1 < ND) {
; #pragma unroll
;                   for (int q4 = 0; q4 < 4; ++q4) ka[(d0 + 1) & 1][q4] = *(LAS bf16x8*)(kb + q4 * 32 * KSTR + (d0 + 1) * 32);
;               }
; #pragma unroll
;               for (int q4 = 0; q4 < 4; ++q4) p[q4] = __builtin_amdgcn_mfma_f32_32x32x16_bf16(ka[d0 & 1][q4], qr[d0], d0 == 0 ? negm : p[q4], 0, 0, 0);
;               if (d0 == 0) { if (t + 1 < NT) AT_STORE(cur ^ 1); if (t + 2 < NT) AT_LOAD(t + 2); }
;               __builtin_amdgcn_sched_barrier(0);
;           } }
;         float rma = fmaxf(p[0][0], p[1][0]), rmb = fmaxf(p[2][0], p[3][0]);
; #pragma unroll
;         for (int r = 1; r < 16; ++r) { rma = fmaxf(fmaxf(rma, p[0][r]), p[1][r]); rmb = fmaxf(fmaxf(rmb, p[2][r]), p[3][r]); }
;         float rm = fmaxf(rma, rmb);
;         { const unsigned ru_ = __builtin_bit_cast(unsigned, rm); auto rr_ = __builtin_amdgcn_permlane32_swap(ru_, ru_, false, false);
;           rm = fmaxf(__builtin_bit_cast(float, (unsigned)rr_[0]), __builtin_bit_cast(float, (unsigned)rr_[1])); }
;         if (t == 0 || __any(rm > 8.0f)) {
;             const float dl = (t == 0) ? rm : fmaxf(rm, 0.f), f = __builtin_amdgcn_exp2f(-dl);
;             mhat += dl;
; #pragma unroll
;             for (int r = 0; r < 16; ++r) { p[0][r] -= dl; p[1][r] -= dl; p[2][r] -= dl; p[3][r] -= dl; negm[r] = -mhat; }
;             if (hi == 0) wsf[r32] = f;
;             asm volatile("s_waitcnt lgkmcnt(0)" ::: "memory");
; #pragma unroll
;             for (int r = 0; r < 16; ++r) { const float fr = wsf[crow(r, hi)]; o0[r] *= fr; o1[r] *= fr; ol[r] *= fr; }
;             asm volatile("s_waitcnt lgkmcnt(0)" ::: "memory");
;         }
;         u32x4 pw[8];
;         { LAS unsigned char* vb = lds + cur * AT_VBUF + vfo;
;     ...
;           bf16x8 vfa[2], vfb[2];
;           vfa[0] = AT_VF(0, 0); vfa[1] = AT_VF(1, 0);
;           AT_EXPQ(0);
.LBB0_154:
	s_waitcnt lgkmcnt(7)
	v_mfma_f32_32x32x16_bf16 v[2:17], v[80:83], v[134:137], v[2:17]
	s_waitcnt lgkmcnt(6)
	v_mfma_f32_32x32x16_bf16 v[18:33], v[76:79], v[134:137], v[18:33]
	s_waitcnt lgkmcnt(5)
	v_mfma_f32_32x32x16_bf16 v[34:49], v[72:75], v[134:137], v[34:49]
	ds_read_b128 v[72:75], v242 offset:64
	ds_read_b128 v[76:79], v242 offset:4672
	ds_read_b128 v[80:83], v242 offset:9280
	ds_read_b128 v[84:87], v242 offset:13888
	s_waitcnt lgkmcnt(8)
	v_mfma_f32_32x32x16_bf16 v[52:67], v[68:71], v[134:137], v[52:67]
	s_waitcnt lgkmcnt(3)
	v_mfma_f32_32x32x16_bf16 v[2:17], v[72:75], v[138:141], v[2:17]
	s_waitcnt lgkmcnt(2)
	v_mfma_f32_32x32x16_bf16 v[18:33], v[76:79], v[138:141], v[18:33]
	s_waitcnt lgkmcnt(1)
	v_mfma_f32_32x32x16_bf16 v[34:49], v[80:83], v[138:141], v[34:49]
	ds_read_b128 v[68:71], v242 offset:96
	ds_read_b128 v[72:75], v242 offset:4704
	ds_read_b128 v[76:79], v242 offset:9312
	ds_read_b128 v[80:83], v242 offset:13920
	s_waitcnt lgkmcnt(4)
	v_mfma_f32_32x32x16_bf16 v[52:67], v[84:87], v[138:141], v[52:67]
	s_waitcnt lgkmcnt(3)
	v_mfma_f32_32x32x16_bf16 v[2:17], v[68:71], v[142:145], v[2:17]
	s_waitcnt lgkmcnt(2)
	v_mfma_f32_32x32x16_bf16 v[18:33], v[72:75], v[142:145], v[18:33]
	s_waitcnt lgkmcnt(1)
	v_mfma_f32_32x32x16_bf16 v[34:49], v[76:79], v[142:145], v[34:49]
	s_waitcnt lgkmcnt(0)
	v_mfma_f32_32x32x16_bf16 v[52:67], v[80:83], v[142:145], v[52:67]
	s_nop 11
	v_max_f32_e32 v0, v52, v52
	v_max_f32_e32 v50, v34, v34
	v_max_f32_e32 v0, v50, v0
	v_max3_f32 v50, v2, v18, v3
	v_max3_f32 v0, v0, v35, v53
	v_max3_f32 v50, v50, v19, v4
	v_max3_f32 v0, v0, v36, v54
	v_max3_f32 v50, v50, v20, v5
	v_max3_f32 v0, v0, v37, v55
	v_max3_f32 v50, v50, v21, v6
	v_max3_f32 v0, v0, v38, v56
	v_max3_f32 v50, v50, v22, v7
	v_max3_f32 v0, v0, v39, v57
	v_max3_f32 v50, v50, v23, v8
	v_max3_f32 v0, v0, v40, v58
	v_max3_f32 v50, v50, v24, v9
	v_max3_f32 v0, v0, v41, v59
	v_max3_f32 v50, v50, v25, v10
	v_max3_f32 v0, v0, v42, v60
	v_max3_f32 v50, v50, v26, v11
	v_max3_f32 v0, v0, v43, v61
	v_max3_f32 v50, v50, v27, v12
	v_max3_f32 v0, v0, v44, v62
	v_max3_f32 v50, v50, v28, v13
	v_max3_f32 v0, v0, v45, v63
	v_max3_f32 v50, v50, v29, v14
	v_max3_f32 v0, v0, v46, v64
	v_max3_f32 v50, v50, v30, v15
	v_max3_f32 v0, v0, v47, v65
	v_max3_f32 v50, v50, v31, v16
	v_max3_f32 v0, v0, v48, v66
	v_max3_f32 v50, v50, v32, v17
	v_max3_f32 v0, v0, v49, v67
	v_max3_f32 v0, v50, v33, v0
	v_mov_b32_e32 v50, v0
	s_nop 1
	v_permlane32_swap_b32_e32 v0, v50
	v_max_f32_e32 v50, v50, v50
	v_max_f32_e32 v0, v0, v0
	v_max_f32_e32 v0, v0, v50
	s_and_saveexec_b64 s[22:23], s[40:41]
	v_exp_f32_e64 v50, -v0
	ds_write_b32 v238, v50
	s_or_b64 exec, exec, s[22:23]
	s_waitcnt lgkmcnt(0)
	v_add_u32_e32 v185, s63, v236
	v_sub_f32_e32 v51, v2, v0
	v_sub_f32_e32 v76, v18, v0
	v_sub_f32_e32 v78, v52, v0
	v_sub_f32_e32 v52, v3, v0
	v_sub_f32_e32 v79, v19, v0
	v_sub_f32_e32 v81, v53, v0
	v_sub_f32_e32 v53, v4, v0
	v_sub_f32_e32 v82, v20, v0
	v_sub_f32_e32 v84, v54, v0
	v_sub_f32_e32 v54, v5, v0
	v_sub_f32_e32 v85, v21, v0
	v_sub_f32_e32 v87, v55, v0
	v_sub_f32_e32 v55, v6, v0
	v_sub_f32_e32 v88, v22, v0
	v_sub_f32_e32 v89, v38, v0
	v_sub_f32_e32 v38, v7, v0
	v_sub_f32_e32 v91, v23, v0
	v_sub_f32_e32 v92, v39, v0
	v_sub_f32_e32 v39, v8, v0
	v_sub_f32_e32 v94, v24, v0
	v_sub_f32_e32 v95, v40, v0
	v_sub_f32_e32 v40, v9, v0
	v_sub_f32_e32 v97, v25, v0
	ds_read_b128 v[2:5], v185 offset:64
	ds_read_b128 v[6:9], v185 offset:96
	ds_read_b128 v[18:21], v185
	ds_read_b128 v[22:25], v185 offset:32
	s_waitcnt lgkmcnt(0)
	v_sub_f32_e32 v77, v34, v0
	v_sub_f32_e32 v80, v35, v0
	v_sub_f32_e32 v83, v36, v0
	v_sub_f32_e32 v86, v37, v0
	v_sub_f32_e32 v90, v56, v0
	v_sub_f32_e32 v93, v57, v0
	v_sub_f32_e32 v96, v58, v0
	v_sub_f32_e32 v99, v59, v0
	ds_read_b64_tr_b16 v[34:35], v243 offset:53248
	ds_read_b64_tr_b16 v[36:37], v243 offset:53760
	ds_read_b64_tr_b16 v[56:57], v243 offset:61440
	ds_read_b64_tr_b16 v[58:59], v243 offset:61952
	v_sub_f32_e32 v98, v41, v0
	v_sub_f32_e32 v41, v10, v0
	v_sub_f32_e32 v72, v26, v0
	v_sub_f32_e32 v26, v11, v0
	v_sub_f32_e32 v73, v27, v0
	v_sub_f32_e32 v27, v12, v0
	v_sub_f32_e32 v74, v28, v0
	v_sub_f32_e32 v28, v13, v0
	v_sub_f32_e32 v75, v29, v0
	v_sub_f32_e32 v29, v14, v0
	v_sub_f32_e32 v108, v30, v0
	v_sub_f32_e32 v30, v15, v0
	v_sub_f32_e32 v111, v31, v0
	v_sub_f32_e32 v31, v16, v0
	v_sub_f32_e32 v114, v32, v0
	v_sub_f32_e32 v32, v17, v0
	v_sub_f32_e32 v117, v33, v0
	s_waitcnt lgkmcnt(6)
	v_pk_mul_f32 v[16:17], v[8:9], 0 op_sel_hi:[1,0]
	v_pk_mul_f32 v[12:13], v[4:5], 0 op_sel_hi:[1,0]
	s_waitcnt lgkmcnt(4)
	v_pk_mul_f32 v[8:9], v[24:25], 0 op_sel_hi:[1,0]
	v_pk_mul_f32 v[4:5], v[20:21], 0 op_sel_hi:[1,0]
	v_pk_mul_f32 v[14:15], v[6:7], 0 op_sel_hi:[1,0]
	v_pk_mul_f32 v[10:11], v[2:3], 0 op_sel_hi:[1,0]
	v_pk_mul_f32 v[6:7], v[22:23], 0 op_sel_hi:[1,0]
	v_pk_mul_f32 v[2:3], v[18:19], 0 op_sel_hi:[1,0]
	v_exp_f32_e32 v18, v51
	v_exp_f32_e32 v19, v52
	v_exp_f32_e32 v20, v53
	v_exp_f32_e32 v21, v54
	v_exp_f32_e32 v22, v55
	v_exp_f32_e32 v23, v38
	v_exp_f32_e32 v24, v39
	v_exp_f32_e32 v25, v40
	v_exp_f32_e32 v33, v41
	v_exp_f32_e32 v26, v26
	v_exp_f32_e32 v27, v27
	v_exp_f32_e32 v28, v28
	v_exp_f32_e32 v29, v29
	v_exp_f32_e32 v30, v30
	v_exp_f32_e32 v31, v31
	v_exp_f32_e32 v32, v32
	v_add_f32_e32 v184, 0, v0
	v_xor_b32_e32 v50, 0x80000000, v184
	v_sub_f32_e32 v101, v60, v0
	v_sub_f32_e32 v103, v61, v0
	v_sub_f32_e32 v105, v62, v0
	v_sub_f32_e32 v107, v63, v0
	v_sub_f32_e32 v110, v64, v0
	v_sub_f32_e32 v113, v65, v0
	s_lshr_b32 s4, s4, 7
	v_cvt_pk_bf16_f32 v60, v18, v19
	v_cvt_pk_bf16_f32 v61, v20, v21
	v_cvt_pk_bf16_f32 v62, v22, v23
	v_cvt_pk_bf16_f32 v63, v24, v25
	v_cvt_pk_bf16_f32 v64, v33, v26
	v_cvt_pk_bf16_f32 v65, v27, v28
	v_sub_f32_e32 v100, v42, v0
	v_sub_f32_e32 v102, v43, v0
	v_sub_f32_e32 v104, v44, v0
	v_sub_f32_e32 v106, v45, v0
	v_sub_f32_e32 v109, v46, v0
	v_sub_f32_e32 v112, v47, v0
	v_sub_f32_e32 v115, v48, v0
	v_sub_f32_e32 v116, v66, v0
	v_sub_f32_e32 v118, v49, v0
	v_sub_f32_e32 v0, v67, v0
	v_cvt_pk_bf16_f32 v66, v29, v30
	v_cvt_pk_bf16_f32 v67, v31, v32
	s_waitcnt lgkmcnt(2)
; #define AT_PVK(ks, VF) do { o0 = __builtin_amdgcn_mfma_f32_32x32x16_bf16(__builtin_bit_cast(bf16x8, pw[ks]), VF[0], o0, 0, 0, 0); \
;             o1 = __builtin_amdgcn_mfma_f32_32x32x16_bf16(__builtin_bit_cast(bf16x8, pw[ks]), VF[1], o1, 0, 0, 0); \
;             ol = __builtin_amdgcn_mfma_f32_32x32x16_bf16(__builtin_bit_cast(bf16x8, pw[ks]), ones, ol, 0, 0, 0); } while (0)
; template <int DK>
; __device__ __forceinline__ void attn_unit(LAS unsigned char* lds, const GAS bf16* Qp, const GAS bf16* Kp, const GAS bf16* Vp, GAS bf16* Yp, int b, int j, int nkeys, int tid, int lane, int wave) {
;     ...
;           vfa[0] = AT_VF(0, 0); vfa[1] = AT_VF(1, 0);
;           AT_EXPQ(0);
;           __builtin_amdgcn_sched_barrier(0);
; #pragma unroll
;           for (int q4 = 0; q4 < 4; ++q4) {
;               vfb[0] = AT_VF(0, 2 * q4 + 1); vfb[1] = AT_VF(1, 2 * q4 + 1);
;               AT_PVK(2 * q4, vfa);
;               if (q4 + 1 < 4) { AT_EXPQ(q4 + 1); vfa[0] = AT_VF(0, 2 * q4 + 2); vfa[1] = AT_VF(1, 2 * q4 + 2); }
;               AT_PVK(2 * q4 + 1, vfb);
;               __builtin_amdgcn_sched_barrier(0);
;           }
;     ...
;         }
;         __syncthreads();
	v_mfma_f32_32x32x16_bf16 v[18:33], v[60:63], v[34:37], v[2:17]
	s_mov_b32 s69, s68
	s_mov_b32 s70, s68
	s_mov_b32 s71, s68
	v_mov_b64_e32 v[52:53], s[68:69]
	v_mov_b64_e32 v[54:55], s[70:71]
	ds_read_b64_tr_b16 v[68:69], v243 offset:54272
	ds_read_b64_tr_b16 v[70:71], v243 offset:54784
	v_exp_f32_e32 v51, v72
	s_waitcnt lgkmcnt(2)
	v_mfma_f32_32x32x16_bf16 v[34:49], v[60:63], v[56:59], v[2:17]
	v_exp_f32_e32 v56, v73
	v_exp_f32_e32 v57, v74
	v_exp_f32_e32 v58, v75
	v_exp_f32_e32 v59, v108
	v_exp_f32_e32 v72, v111
	v_exp_f32_e32 v73, v114
	v_cvt_pk_bf16_f32 v57, v57, v58
	v_mfma_f32_32x32x16_bf16 v[2:17], v[60:63], v[52:55], v[2:17]
	v_exp_f32_e32 v60, v117
	v_cvt_pk_bf16_f32 v58, v59, v72
	v_cvt_pk_bf16_f32 v56, v51, v56
	v_exp_f32_e32 v51, v76
	v_cvt_pk_bf16_f32 v59, v73, v60
	ds_read_b64_tr_b16 v[60:61], v243 offset:55296
	ds_read_b64_tr_b16 v[62:63], v243 offset:55808
	v_exp_f32_e32 v76, v79
	s_waitcnt lgkmcnt(2)
	v_mfma_f32_32x32x16_bf16 v[18:33], v[64:67], v[68:71], v[18:33]
	ds_read_b64_tr_b16 v[68:69], v243 offset:62464
	ds_read_b64_tr_b16 v[70:71], v243 offset:62976
	ds_read_b64_tr_b16 v[72:73], v243 offset:63488
	ds_read_b64_tr_b16 v[74:75], v243 offset:64000
	v_exp_f32_e32 v79, v82
	v_exp_f32_e32 v82, v85
	v_exp_f32_e32 v85, v88
	v_exp_f32_e32 v88, v97
	s_waitcnt lgkmcnt(2)
	v_mfma_f32_32x32x16_bf16 v[34:49], v[64:67], v[68:71], v[34:49]
	v_exp_f32_e32 v70, v91
	v_exp_f32_e32 v71, v94
	v_cvt_pk_bf16_f32 v68, v51, v76
	v_cvt_pk_bf16_f32 v69, v79, v82
	v_cvt_pk_bf16_f32 v70, v85, v70
	v_cvt_pk_bf16_f32 v71, v71, v88
	v_mfma_f32_32x32x16_bf16 v[2:17], v[64:67], v[52:55], v[2:17]
	s_nop 0
	v_mfma_f32_32x32x16_bf16 v[18:33], v[68:71], v[60:63], v[18:33]
	ds_read_b64_tr_b16 v[60:61], v243 offset:56320
	ds_read_b64_tr_b16 v[62:63], v243 offset:56832
	v_exp_f32_e32 v65, v104
	v_exp_f32_e32 v66, v106
	v_exp_f32_e32 v67, v109
	v_exp_f32_e32 v51, v100
	v_exp_f32_e32 v64, v102
	v_cvt_pk_bf16_f32 v65, v65, v66
	s_waitcnt lgkmcnt(2)
	v_mfma_f32_32x32x16_bf16 v[34:49], v[68:71], v[72:75], v[34:49]
	v_exp_f32_e32 v72, v112
	v_exp_f32_e32 v73, v115
	v_cvt_pk_bf16_f32 v64, v51, v64
	v_exp_f32_e32 v51, v77
	v_cvt_pk_bf16_f32 v66, v67, v72
	v_exp_f32_e32 v76, v80
	v_exp_f32_e32 v77, v83
	v_mfma_f32_32x32x16_bf16 v[2:17], v[68:71], v[52:55], v[2:17]
	v_exp_f32_e32 v68, v118
	v_exp_f32_e32 v79, v86
	v_exp_f32_e32 v80, v89
	v_exp_f32_e32 v82, v98
	v_cvt_pk_bf16_f32 v67, v73, v68
	ds_read_b64_tr_b16 v[68:69], v243 offset:57344
	ds_read_b64_tr_b16 v[70:71], v243 offset:57856
	s_waitcnt lgkmcnt(2)
	v_mfma_f32_32x32x16_bf16 v[18:33], v[56:59], v[60:63], v[18:33]
	ds_read_b64_tr_b16 v[60:61], v243 offset:64512
	ds_read_b64_tr_b16 v[62:63], v243 offset:65024
	ds_read_b64_tr_b16 v[72:73], v244 offset:12288
	ds_read_b64_tr_b16 v[74:75], v244 offset:12800
	s_waitcnt lgkmcnt(2)
	v_mfma_f32_32x32x16_bf16 v[34:49], v[56:59], v[60:63], v[34:49]
	v_exp_f32_e32 v62, v92
	v_exp_f32_e32 v63, v95
	v_cvt_pk_bf16_f32 v60, v51, v76
	v_cvt_pk_bf16_f32 v61, v77, v79
	v_cvt_pk_bf16_f32 v62, v80, v62
	v_cvt_pk_bf16_f32 v63, v63, v82
	v_mfma_f32_32x32x16_bf16 v[2:17], v[56:59], v[52:55], v[2:17]
	s_nop 0
	v_mfma_f32_32x32x16_bf16 v[18:33], v[60:63], v[68:71], v[18:33]
	ds_read_b64_tr_b16 v[56:57], v243 offset:58368
	ds_read_b64_tr_b16 v[58:59], v243 offset:58880
	v_exp_f32_e32 v51, v101
	v_exp_f32_e32 v68, v103
	v_exp_f32_e32 v69, v105
	v_exp_f32_e32 v70, v107
	v_exp_f32_e32 v71, v110
	v_exp_f32_e32 v0, v0
	s_waitcnt lgkmcnt(2)
	v_mfma_f32_32x32x16_bf16 v[34:49], v[60:63], v[72:75], v[34:49]
	v_exp_f32_e32 v72, v113
	v_exp_f32_e32 v73, v116
	v_exp_f32_e32 v76, v84
	v_exp_f32_e32 v77, v87
	v_exp_f32_e32 v79, v99
	v_mfma_f32_32x32x16_bf16 v[2:17], v[60:63], v[52:55], v[2:17]
	v_cvt_pk_bf16_f32 v60, v51, v68
	v_cvt_pk_bf16_f32 v61, v69, v70
	v_cvt_pk_bf16_f32 v62, v71, v72
	v_cvt_pk_bf16_f32 v63, v73, v0
	ds_read_b64_tr_b16 v[68:69], v243 offset:59392
	ds_read_b64_tr_b16 v[70:71], v243 offset:59904
	v_exp_f32_e32 v0, v78
	v_exp_f32_e32 v51, v81
	s_waitcnt lgkmcnt(2)
	v_mfma_f32_32x32x16_bf16 v[18:33], v[64:67], v[56:59], v[18:33]
	ds_read_b64_tr_b16 v[56:57], v244 offset:13312
	ds_read_b64_tr_b16 v[58:59], v244 offset:13824
	ds_read_b64_tr_b16 v[72:73], v244 offset:14336
	ds_read_b64_tr_b16 v[74:75], v244 offset:14848
	v_exp_f32_e32 v78, v90
	s_waitcnt lgkmcnt(2)
	v_mfma_f32_32x32x16_bf16 v[34:49], v[64:67], v[56:59], v[34:49]
	v_exp_f32_e32 v58, v93
	v_exp_f32_e32 v59, v96
	v_cvt_pk_bf16_f32 v56, v0, v51
	v_cvt_pk_bf16_f32 v57, v76, v77
	v_cvt_pk_bf16_f32 v58, v78, v58
	v_cvt_pk_bf16_f32 v59, v59, v79
	v_mfma_f32_32x32x16_bf16 v[2:17], v[64:67], v[52:55], v[2:17]
	s_nop 0
	v_mfma_f32_32x32x16_bf16 v[18:33], v[56:59], v[68:71], v[18:33]
	s_waitcnt lgkmcnt(0)
	v_mfma_f32_32x32x16_bf16 v[34:49], v[56:59], v[72:75], v[34:49]
	v_mfma_f32_32x32x16_bf16 v[2:17], v[56:59], v[52:55], v[2:17]
	ds_read_b64_tr_b16 v[56:57], v243 offset:60416
	ds_read_b64_tr_b16 v[58:59], v243 offset:60928
	ds_read_b64_tr_b16 v[64:65], v244 offset:15360
	ds_read_b64_tr_b16 v[66:67], v244 offset:15872
	s_waitcnt lgkmcnt(2)
	v_mfma_f32_32x32x16_bf16 v[18:33], v[60:63], v[56:59], v[18:33]
	s_waitcnt lgkmcnt(0)
	v_mfma_f32_32x32x16_bf16 v[34:49], v[60:63], v[64:67], v[34:49]
	v_mfma_f32_32x32x16_bf16 v[2:17], v[60:63], v[52:55], v[2:17]
	v_mad_i64_i32 v[180:181], s[8:9], s6, v213, v[208:209]
	v_mad_i64_i32 v[182:183], s[6:7], s6, v213, v[210:211]
	s_lshl_b32 s6, s4, 14
	s_add_u32 s6, s6, 0xffffc000
	s_mov_b64 s[22:23], 0
	s_mov_b32 s7, 3
	v_mov_b32_e32 v51, v50
	v_mov_b32_e32 v52, v50
	v_mov_b32_e32 v53, v50
	v_mov_b32_e32 v54, v50
	v_mov_b32_e32 v55, v50
	v_mov_b32_e32 v56, v50
	v_mov_b32_e32 v57, v50
	v_mov_b32_e32 v58, v50
	v_mov_b32_e32 v59, v50
	v_mov_b32_e32 v60, v50
	v_mov_b32_e32 v61, v50
	v_mov_b32_e32 v62, v50
	v_mov_b32_e32 v63, v50
	v_mov_b32_e32 v64, v50
	v_mov_b32_e32 v65, v50
	s_add_i32 s8, s7, -2
	s_and_b32 s8, s8, 1
	s_mul_i32 s9, s8, 0x6800
	v_add_u32_e32 v0, s9, v242
	s_barrier
	s_cmp_lt_u32 s97, 4
	s_cbranch_scc1 .Lprio_g
	s_setprio 1

; #define LAS __attribute__((address_space(3)))
; #define AT_PVK(ks, VF) do { o0 = __builtin_amdgcn_mfma_f32_32x32x16_bf16(__builtin_bit_cast(bf16x8, pw[ks]), VF[0], o0, 0, 0, 0); \
;             o1 = __builtin_amdgcn_mfma_f32_32x32x16_bf16(__builtin_bit_cast(bf16x8, pw[ks]), VF[1], o1, 0, 0, 0); \
;             ol = __builtin_amdgcn_mfma_f32_32x32x16_bf16(__builtin_bit_cast(bf16x8, pw[ks]), ones, ol, 0, 0, 0); } while (0)
; template <int DK>
; __device__ __forceinline__ void attn_unit(LAS unsigned char* lds, const GAS bf16* Qp, const GAS bf16* Kp, const GAS bf16* Vp, GAS bf16* Yp, int b, int j, int nkeys, int tid, int lane, int wave) {
;     ...
;         u32x4 pw[8];
;         { LAS unsigned char* vb = lds + cur * AT_VBUF + vfo;
;     ...
;           bf16x8 vfa[2], vfb[2];
;           vfa[0] = AT_VF(0, 0); vfa[1] = AT_VF(1, 0);
;           AT_EXPQ(0);
;           __builtin_amdgcn_sched_barrier(0);
; #pragma unroll
;           for (int q4 = 0; q4 < 4; ++q4) {
;               vfb[0] = AT_VF(0, 2 * q4 + 1); vfb[1] = AT_VF(1, 2 * q4 + 1);
;               AT_PVK(2 * q4, vfa);
;               if (q4 + 1 < 4) { AT_EXPQ(q4 + 1); vfa[0] = AT_VF(0, 2 * q4 + 2); vfa[1] = AT_VF(1, 2 * q4 + 2); }
;               AT_PVK(2 * q4 + 1, vfb);
;               __builtin_amdgcn_sched_barrier(0);
;           }
;     ...
;         }
;         __syncthreads();
.LBB0_158:
	v_lshl_add_u32 v0, s8, 14, v243
	ds_read_b64_tr_b16 v[162:163], v0 offset:53248
	ds_read_b64_tr_b16 v[164:165], v0 offset:53760
	ds_read_b64_tr_b16 v[166:167], v0 offset:61440
	ds_read_b64_tr_b16 v[168:169], v0 offset:61952
	v_exp_f32_e32 v114, v114
	v_exp_f32_e32 v115, v115
	v_exp_f32_e32 v116, v116
	v_exp_f32_e32 v117, v117
	v_exp_f32_e32 v171, v118
	v_exp_f32_e32 v172, v119
	v_exp_f32_e32 v173, v120
	v_exp_f32_e32 v121, v121
	v_exp_f32_e32 v122, v122
	v_exp_f32_e32 v123, v123
	v_exp_f32_e32 v124, v124
	v_exp_f32_e32 v125, v125
	v_exp_f32_e32 v126, v126
	v_exp_f32_e32 v127, v127
	v_exp_f32_e32 v128, v128
	v_exp_f32_e32 v129, v129
	v_add_u32_e32 v170, 0xd000, v0
	v_cvt_pk_bf16_f32 v118, v114, v115
	v_cvt_pk_bf16_f32 v119, v116, v117
	v_cvt_pk_bf16_f32 v120, v171, v172
	v_cvt_pk_bf16_f32 v121, v173, v121
	v_cvt_pk_bf16_f32 v122, v122, v123
	v_cvt_pk_bf16_f32 v123, v124, v125
	v_cvt_pk_bf16_f32 v124, v126, v127
	v_cvt_pk_bf16_f32 v125, v128, v129
	s_waitcnt lgkmcnt(2)
	v_mfma_f32_32x32x16_bf16 v[18:33], v[118:121], v[162:165], v[18:33]
	s_mov_b32 s70, s68
	s_mov_b32 s71, s68
	s_mov_b32 s69, s68
	v_mov_b64_e32 v[116:117], s[70:71]
	v_mov_b64_e32 v[114:115], s[68:69]
	ds_read_b64_tr_b16 v[126:127], v0 offset:54272
	ds_read_b64_tr_b16 v[128:129], v0 offset:54784
	v_exp_f32_e32 v106, v106
	s_waitcnt lgkmcnt(2)
	v_mfma_f32_32x32x16_bf16 v[34:49], v[118:121], v[166:169], v[34:49]
	v_exp_f32_e32 v107, v107
	v_exp_f32_e32 v108, v108
	v_exp_f32_e32 v109, v109
	v_exp_f32_e32 v110, v110
	v_exp_f32_e32 v111, v111
	v_exp_f32_e32 v112, v112
	v_exp_f32_e32 v113, v113
	v_mfma_f32_32x32x16_bf16 v[2:17], v[118:121], v[114:117], v[2:17]
	v_cvt_pk_bf16_f32 v106, v106, v107
	v_cvt_pk_bf16_f32 v107, v108, v109
	v_cvt_pk_bf16_f32 v108, v110, v111
	v_cvt_pk_bf16_f32 v109, v112, v113
	ds_read_b64_tr_b16 v[110:111], v0 offset:55296
	ds_read_b64_tr_b16 v[112:113], v0 offset:55808
	v_exp_f32_e32 v98, v98
	v_exp_f32_e32 v99, v99
	s_waitcnt lgkmcnt(2)
	v_mfma_f32_32x32x16_bf16 v[18:33], v[122:125], v[126:129], v[18:33]
	ds_read_b64_tr_b16 v[118:119], v0 offset:62464
	ds_read_b64_tr_b16 v[120:121], v0 offset:62976
	ds_read_b64_tr_b16 v[126:127], v0 offset:63488
	ds_read_b64_tr_b16 v[128:129], v0 offset:64000
	v_exp_f32_e32 v100, v100
	v_exp_f32_e32 v101, v101
	v_exp_f32_e32 v102, v102
	v_exp_f32_e32 v103, v103
	v_exp_f32_e32 v104, v104
	v_exp_f32_e32 v105, v105
	s_waitcnt lgkmcnt(2)
	v_mfma_f32_32x32x16_bf16 v[34:49], v[122:125], v[118:121], v[34:49]
	v_cvt_pk_bf16_f32 v98, v98, v99
	v_cvt_pk_bf16_f32 v99, v100, v101
	v_cvt_pk_bf16_f32 v100, v102, v103
	v_cvt_pk_bf16_f32 v101, v104, v105
	v_mfma_f32_32x32x16_bf16 v[2:17], v[122:125], v[114:117], v[2:17]
	s_nop 0
	v_mfma_f32_32x32x16_bf16 v[18:33], v[98:101], v[110:113], v[18:33]
	ds_read_b64_tr_b16 v[102:103], v0 offset:56320
	ds_read_b64_tr_b16 v[104:105], v0 offset:56832
	v_exp_f32_e32 v90, v90
	v_exp_f32_e32 v91, v91
	v_exp_f32_e32 v92, v92
	v_exp_f32_e32 v93, v93
	v_exp_f32_e32 v94, v94
	v_exp_f32_e32 v95, v95
	s_waitcnt lgkmcnt(2)
	v_mfma_f32_32x32x16_bf16 v[34:49], v[98:101], v[126:129], v[34:49]
	v_exp_f32_e32 v96, v96
	v_exp_f32_e32 v97, v97
	v_cvt_pk_bf16_f32 v90, v90, v91
	v_cvt_pk_bf16_f32 v91, v92, v93
	v_cvt_pk_bf16_f32 v92, v94, v95
	v_cvt_pk_bf16_f32 v93, v96, v97
	ds_read_b64_tr_b16 v[94:95], v0 offset:57344
	ds_read_b64_tr_b16 v[96:97], v0 offset:57856
	v_mfma_f32_32x32x16_bf16 v[2:17], v[98:101], v[114:117], v[2:17]
	v_exp_f32_e32 v82, v82
	v_exp_f32_e32 v83, v83
	v_exp_f32_e32 v84, v84
	v_exp_f32_e32 v85, v85
	v_exp_f32_e32 v86, v86
	v_exp_f32_e32 v87, v87
	v_exp_f32_e32 v88, v88
	s_waitcnt lgkmcnt(2)
	v_mfma_f32_32x32x16_bf16 v[18:33], v[106:109], v[102:105], v[18:33]
	ds_read_b64_tr_b16 v[98:99], v0 offset:64512
	ds_read_b64_tr_b16 v[100:101], v0 offset:65024
	ds_read_b64_tr_b16 v[102:103], v170 offset:12288
	ds_read_b64_tr_b16 v[104:105], v170 offset:12800
	v_exp_f32_e32 v89, v89
	v_cvt_pk_bf16_f32 v82, v82, v83
	v_cvt_pk_bf16_f32 v83, v84, v85
	v_cvt_pk_bf16_f32 v84, v86, v87
	v_cvt_pk_bf16_f32 v85, v88, v89
	s_waitcnt lgkmcnt(2)
	v_mfma_f32_32x32x16_bf16 v[34:49], v[106:109], v[98:101], v[34:49]
	v_mfma_f32_32x32x16_bf16 v[2:17], v[106:109], v[114:117], v[2:17]
	v_mfma_f32_32x32x16_bf16 v[18:33], v[82:85], v[94:97], v[18:33]
	ds_read_b64_tr_b16 v[86:87], v0 offset:58368
	ds_read_b64_tr_b16 v[88:89], v0 offset:58880
	v_exp_f32_e32 v74, v74
	v_exp_f32_e32 v75, v75
	v_exp_f32_e32 v76, v76
	v_exp_f32_e32 v77, v77
	v_exp_f32_e32 v78, v78
	v_exp_f32_e32 v79, v79
	s_waitcnt lgkmcnt(2)
	v_mfma_f32_32x32x16_bf16 v[34:49], v[82:85], v[102:105], v[34:49]
	v_exp_f32_e32 v80, v80
	v_exp_f32_e32 v81, v81
	v_cvt_pk_bf16_f32 v74, v74, v75
	v_cvt_pk_bf16_f32 v75, v76, v77
	v_cvt_pk_bf16_f32 v76, v78, v79
	v_cvt_pk_bf16_f32 v77, v80, v81
	ds_read_b64_tr_b16 v[78:79], v0 offset:59392
	ds_read_b64_tr_b16 v[80:81], v0 offset:59904
	v_mfma_f32_32x32x16_bf16 v[2:17], v[82:85], v[114:117], v[2:17]
	v_exp_f32_e32 v66, v66
	v_exp_f32_e32 v67, v67
	v_exp_f32_e32 v68, v68
	v_exp_f32_e32 v69, v69
	v_exp_f32_e32 v70, v70
	v_exp_f32_e32 v71, v71
	v_exp_f32_e32 v72, v72
	s_waitcnt lgkmcnt(2)
	v_mfma_f32_32x32x16_bf16 v[18:33], v[90:93], v[86:89], v[18:33]
	ds_read_b64_tr_b16 v[82:83], v170 offset:13312
	ds_read_b64_tr_b16 v[84:85], v170 offset:13824
	ds_read_b64_tr_b16 v[86:87], v170 offset:14336
	ds_read_b64_tr_b16 v[88:89], v170 offset:14848
	v_exp_f32_e32 v73, v73
	v_cvt_pk_bf16_f32 v66, v66, v67
	v_cvt_pk_bf16_f32 v67, v68, v69
	v_cvt_pk_bf16_f32 v68, v70, v71
	v_cvt_pk_bf16_f32 v69, v72, v73
	s_waitcnt lgkmcnt(2)
	v_mfma_f32_32x32x16_bf16 v[34:49], v[90:93], v[82:85], v[34:49]
	v_mfma_f32_32x32x16_bf16 v[2:17], v[90:93], v[114:117], v[2:17]
	v_mfma_f32_32x32x16_bf16 v[18:33], v[66:69], v[78:81], v[18:33]
	s_waitcnt lgkmcnt(0)
	v_mfma_f32_32x32x16_bf16 v[34:49], v[66:69], v[86:89], v[34:49]
	v_mfma_f32_32x32x16_bf16 v[2:17], v[66:69], v[114:117], v[2:17]
	ds_read_b64_tr_b16 v[66:67], v0 offset:60416
	ds_read_b64_tr_b16 v[68:69], v0 offset:60928
	ds_read_b64_tr_b16 v[70:71], v170 offset:15360
	ds_read_b64_tr_b16 v[72:73], v170 offset:15872
	s_waitcnt lgkmcnt(2)
	v_mfma_f32_32x32x16_bf16 v[18:33], v[74:77], v[66:69], v[18:33]
	s_waitcnt lgkmcnt(0)
	v_mfma_f32_32x32x16_bf16 v[34:49], v[74:77], v[70:73], v[34:49]
	v_mfma_f32_32x32x16_bf16 v[2:17], v[74:77], v[114:117], v[2:17]
	s_add_u32 s22, s22, 0x4000
	s_addc_u32 s23, s23, 0
	s_add_i32 s7, s7, 1
	s_add_i32 s8, s7, -2
	s_and_b32 s8, s8, 1
	s_mul_i32 s9, s8, 0x6800
	v_add_u32_e32 v0, s9, v242
	s_cmp_lg_u32 s6, s22
	s_barrier
	s_cbranch_scc0 .LBB0_166
; #define LAS __attribute__((address_space(3)))
; #define AT_LOAD(t) do { const GAS u32x4* Kg_ = (const GAS u32x4*)(Kp + (size_t)(t) * 128 * DK); const GAS u32x4* Vg_ = (const GAS u32x4*)(Vp + (size_t)(t) * 128 * 64); \
;         _Pragma("unroll") for (int i_ = 0; i_ < NKC; ++i_) kreg[i_] = Kg_[tid + 512 * i_]; vreg[0] = Vg_[tid]; vreg[1] = Vg_[tid + 512]; } while (0)
; #define AT_STORE(bf_) do { LAS unsigned char* nb_ = lds + (bf_) * AT_KBUF; _Pragma("unroll") for (int i_ = 0; i_ < NKC; ++i_) *(LAS u32x4*)(nb_ + koff[i_]) = kreg[i_]; \
;         *(LAS u32x4*)(lds + (bf_) * AT_VBUF + voff[0]) = vreg[0]; *(LAS u32x4*)(lds + (bf_) * AT_VBUF + voff[1]) = vreg[1]; } while (0)
; template <int DK>
; __device__ __forceinline__ void attn_unit(LAS unsigned char* lds, const GAS bf16* Qp, const GAS bf16* Kp, const GAS bf16* Vp, GAS bf16* Yp, int b, int j, int nkeys, int tid, int lane, int wave) {
;     ...
;         { LAS unsigned char* kb = lds + cur * AT_KBUF + kfo;
;           bf16x8 ka[2][4];
; #pragma unroll
;           for (int q4 = 0; q4 < 4; ++q4) ka[0][q4] = *(LAS bf16x8*)(kb + q4 * 32 * KSTR);
; #pragma unroll
;           for (int d0 = 0; d0 < ND; ++d0) {
;               if (d0 + 1 < ND) {
; #pragma unroll
;                   for (int q4 = 0; q4 < 4; ++q4) ka[(d0 + 1) & 1][q4] = *(LAS bf16x8*)(kb + q4 * 32 * KSTR + (d0 + 1) * 32);
;               }
; #pragma unroll
;               for (int q4 = 0; q4 < 4; ++q4) p[q4] = __builtin_amdgcn_mfma_f32_32x32x16_bf16(ka[d0 & 1][q4], qr[d0], d0 == 0 ? negm : p[q4], 0, 0, 0);
;               if (d0 == 0) { if (t + 1 < NT) AT_STORE(cur ^ 1); if (t + 2 < NT) AT_LOAD(t + 2); }
.LBB0_159:
	ds_read_b128 v[66:69], v0
	ds_read_b128 v[162:165], v0 offset:32
	s_add_i32 s9, s7, -1
	s_cmp_ge_u32 s9, s4
	s_waitcnt lgkmcnt(1)
	v_mfma_f32_32x32x16_bf16 v[114:129], v[66:69], v[130:133], v[50:65]
	ds_read_b128 v[66:69], v0 offset:4608
	ds_read_b128 v[166:169], v0 offset:4640
	s_waitcnt lgkmcnt(1)
	v_mfma_f32_32x32x16_bf16 v[98:113], v[66:69], v[130:133], v[50:65]
	ds_read_b128 v[66:69], v0 offset:9216
	ds_read_b128 v[170:173], v0 offset:9248
	ds_read_b128 v[186:189], v0 offset:13824
	ds_read_b128 v[174:177], v0 offset:13856
	s_waitcnt lgkmcnt(3)
	v_mfma_f32_32x32x16_bf16 v[82:97], v[66:69], v[130:133], v[50:65]
	s_waitcnt lgkmcnt(1)
	v_mfma_f32_32x32x16_bf16 v[66:81], v[186:189], v[130:133], v[50:65]
	s_cbranch_scc1 .LBB0_161
	s_xor_b32 s9, s8, 1
	s_lshl_b32 s10, s9, 14
	s_add_i32 s10, s10, 0
	s_mulk_i32 s9, 0x2800
	v_add_u32_e32 v186, s10, v235
	s_add_i32 s10, s10, s9
	v_add_u32_e32 v187, s10, v240
	s_waitcnt vmcnt(3)
	ds_write_b128 v187, v[146:149]
	v_add_u32_e32 v187, s10, v241
	s_waitcnt vmcnt(2)
	ds_write_b128 v187, v[150:153]
	s_waitcnt vmcnt(1)
	ds_write_b128 v186, v[154:157] offset:53248
	s_waitcnt vmcnt(0)
	ds_write_b128 v186, v[158:161] offset:57344
